# first phase seam: cooperative-groups grid.sync replaced by the kernel's own XCD barrier (flag word published by workgroup 0 after zeroing, registration at the seam)
# speedup vs baseline: 1.0229x; 1.0157x over previous
; #define LAS __attribute__((address_space(3)))
; __global__ void __launch_bounds__(NTHR, 2) mega(P p, int ph_lo, int ph_hi) {
;     ...
;   if (blockIdx.x == 0) { for (int i = threadIdx.x; i < XCD_BAR_WORDS; i += NTHR) p.bar[i] = 0u; }
;   const int nb = gridDim.x, nw = nb * 4;
;   u16* smu = (u16*)smem;
;   const u16* proj = (const u16*)p.H;
;   for (int si = ph_lo; si < ph_hi; ++si) {
;     const int ph = p.seq[si];
;     if (si > ph_lo) { if (si == ph_lo + 1) { grid.sync(); xb = xcd_barrier_post(p.bar, (volatile LAS unsigned*)&xb_words); } else xcd_barrier(xb); }
.LBB0_10:
	s_or_b64 exec, exec, s[6:7]
	s_waitcnt vmcnt(0)
	s_barrier
	v_cmp_eq_u32_e32 vcc, 0, v132
	s_and_saveexec_b64 s[4:5], vcc
	buffer_wbl2 sc1
	s_waitcnt vmcnt(0)
	v_mov_b32_e32 v8, 0x7a3c59e1
	v_mov_b32_e32 v9, 0
	global_store_dword v9, v8, s[34:35] sc0 sc1
	s_waitcnt vmcnt(0)
	s_or_b64 exec, exec, s[4:5]
	s_load_dwordx2 s[8:9], s[0:1], 0x890
	s_waitcnt lgkmcnt(0)
	s_cmp_ge_i32 s8, s9
	s_cbranch_scc0 .LBB0_11
	s_getpc_b64 s[98:99]

; #define LAS __attribute__((address_space(3)))
; __device__ __forceinline__ void xcd_barrier(const XcdBarrier& b) {
;   asm volatile("s_waitcnt vmcnt(0)" ::: "memory");
;   __syncthreads();
;   if (threadIdx.x == 0) {
;     unsigned* bar = b.bar;
;     __builtin_amdgcn_s_waitcnt(0);
;     unsigned nloc = b.st[0], nx = b.st[1];
;     if (nloc == 0u) { xcd_barrier_complete(bar, b.x, nloc, nx); b.st[0] = nloc; b.st[1] = nx; }
; __global__ void __launch_bounds__(NTHR, 2) mega(P p, int ph_lo, int ph_hi) {
;     ...
;   for (int si = ph_lo; si < ph_hi; ++si) {
;     const int ph = p.seq[si];
;     if (si > ph_lo) { if (si == ph_lo + 1) { grid.sync(); xb = xcd_barrier_post(p.bar, (volatile LAS unsigned*)&xb_words); } else xcd_barrier(xb); }
.LBB0_14:
	s_ashr_i32 s4, s59, 31
	s_add_u32 s6, s0, s59
	s_addc_u32 s7, s1, s4
	global_load_ubyte v0, v135, s[6:7] offset:2128
	s_cmp_le_i32 s59, s8
	s_waitcnt vmcnt(0)
	v_readfirstlane_b32 s60, v0
	s_cbranch_scc1 .LBB0_80
	v_readlane_b32 s4, v230, 5
	s_cmp_lg_u32 s59, s4
	s_mov_b64 s[6:7], -1
	s_cbranch_scc1 .Lxb_hr
	s_getreg_b32 s4, hwreg(HW_REG_XCC_ID, 0, 4)
	s_and_b32 s4, s4, 15
	s_nop 0
	v_writelane_b32 v229, s4, 26
	s_mov_b64 s[6:7], exec
	v_readlane_b32 s8, v230, 3
	v_readlane_b32 s9, v230, 4
	s_nop 3
	s_and_b64 s[8:9], s[6:7], s[8:9]
	s_mov_b64 exec, s[8:9]
	s_cbranch_execz .Lxb_fdone
	s_mov_b32 s10, 0
.Lxb_fpoll:
	global_load_dword v0, v135, s[34:35] sc1
	s_waitcnt vmcnt(0)
	v_cmp_eq_u32_e32 vcc, 0x7a3c59e1, v0
	s_nop 1
	s_cbranch_vccnz .Lxb_fok
	s_sleep 1
	s_add_u32 s10, s10, 1
	s_cmp_lt_u32 s10, 0x100000
	s_cbranch_scc1 .Lxb_fpoll
.Lxb_fok:
	s_getreg_b32 s10, hwreg(HW_REG_HW_ID)
	v_readlane_b32 s4, v229, 26
	s_lshr_b32 s10, s10, 8
	s_and_b32 s11, s10, 0xff
	s_and_b32 s12, s11, 0x90
	s_nop 0
	s_nop 0
	s_and_b32 s13, s11, 15
	s_lshr_b32 s14, s11, 5
	s_and_b32 s14, s14, 3
	s_lshl_b32 s14, s14, 4
	s_or_b32 s13, s13, s14
	s_cmp_eq_u32 s12, 0
	s_cselect_b32 s15, 1, 0
	s_cmp_lg_u32 s13, 0
	s_cselect_b32 s14, 1, 0
	s_and_b32 s15, s15, s14
	s_cmp_lt_u32 s4, 8
	s_cselect_b32 s14, 1, 0
	s_and_b32 s15, s15, s14
	s_add_u32 s14, s4, 8
	s_lshl_b32 s14, s14, 6
	s_add_u32 s14, s14, 0x900
	s_add_u32 s14, s14, s13
	s_lshl_b32 s14, s14, 2
	s_cmp_lg_u32 s15, 0
	s_cselect_b32 s14, s14, 0
	s_nop 0
	v_writelane_b32 v229, s14, 58
	s_cbranch_scc0 .Lxb_noreg2
	v_mov_b32_e32 v2, s14
	v_mov_b32_e32 v4, 0x10000
	global_atomic_add v3, v2, v4, s[34:35] sc0
	s_waitcnt vmcnt(0)
.Lxb_noreg2:
	v_readlane_b32 s4, v229, 26
	s_nop 3
	s_lshl_b32 s4, s4, 8
	v_mov_b32_e32 v0, s4
	global_atomic_add v0, v199, s[34:35] offset:1024
	s_waitcnt vmcnt(0)
.Lxb_fdone:
	s_mov_b64 exec, s[6:7]
.Lxb_hr:
	s_waitcnt vmcnt(0)
	s_barrier
	s_mov_b64 s[6:7], exec
	v_readlane_b32 s8, v230, 3
	v_readlane_b32 s9, v230, 4
	s_and_b64 s[8:9], s[6:7], s[8:9]
	s_mov_b64 exec, s[8:9]
	s_cbranch_execz .LBB0_64
	s_waitcnt vmcnt(0) expcnt(0) lgkmcnt(0)
	ds_read_b32 v2, v133
	ds_read_b32 v0, v137
	s_waitcnt lgkmcnt(1)
	v_cmp_ne_u32_e32 vcc, 0, v2
	s_cbranch_vccnz .LBB0_32
	s_mov_b32 s4, 1
	s_branch .LBB0_20

; #define LAS __attribute__((address_space(3)))
; __global__ void __launch_bounds__(NTHR, 2) mega(P p, int ph_lo, int ph_hi) {
;     ...
;   if (blockIdx.x == 0) { for (int i = threadIdx.x; i < XCD_BAR_WORDS; i += NTHR) p.bar[i] = 0u; }
;   const int nb = gridDim.x, nw = nb * 4;
;   u16* smu = (u16*)smem;
;   const u16* proj = (const u16*)p.H;
;   for (int si = ph_lo; si < ph_hi; ++si) {
;     const int ph = p.seq[si];
;     if (si > ph_lo) { if (si == ph_lo + 1) { grid.sync(); xb = xcd_barrier_post(p.bar, (volatile LAS unsigned*)&xb_words); } else xcd_barrier(xb); }
.LBB0_609:
	v_readlane_b32 s2, v230, 0
	s_nop 3
	s_cmp_lg_u32 s2, 0
	s_cbranch_scc1 .Lxb_end
	s_load_dwordx2 s[34:35], s[0:1], 0x230
	v_cmp_eq_u32_e32 vcc, 0, v132
	s_and_saveexec_b64 s[4:5], vcc
	v_mov_b32_e32 v8, 0
	s_waitcnt lgkmcnt(0)
	global_store_dword v8, v8, s[34:35] sc0 sc1
	s_waitcnt vmcnt(0)
